# attention steady loop: K/V DMA addresses as SGPR base + invariant VGPR offsets (no per-iteration 64-bit VALU adds), dropped +0 adds
# speedup vs baseline: 1.0027x; 1.0027x over previous
.LBB0_483:
	s_lshl_b32 s2, s5, 1
	s_ashr_i32 s3, s4, 2
	s_add_i32 s5, s2, s3
	s_lshl_b64 s[2:3], s[88:89], 10
	s_add_u32 s8, s86, s2
	s_addc_u32 s9, s87, s3
	s_lshl_b32 s2, s4, 6
	s_ashr_i32 s3, s2, 31
	s_lshl_b64 s[6:7], s[2:3], 1
	s_add_u32 s8, s8, s6
	s_addc_u32 s9, s9, s7
	s_mul_hi_i32 s2, s5, 0x108000
	s_mul_i32 s5, s5, 0x108000
	s_add_u32 s14, s40, s5
	s_addc_u32 s15, s72, s2
	v_mov_b32_e32 v42, v234
	s_add_u32 s16, s73, s5
	s_addc_u32 s17, s74, s2
	v_readfirstlane_b32 s10, v42
	s_ashr_i32 s2, s10, 6
	s_ashr_i32 s3, s2, 31
	s_lshl_b64 s[4:5], s[2:3], 15
	s_add_u32 s8, s8, s4
	s_addc_u32 s9, s9, s5
	s_and_b32 s5, s10, 0x3fffffc0
	s_lshl_b32 s10, s2, 9
	s_ashr_i32 s11, s10, 31
	s_lshl_b64 s[10:11], s[10:11], 1
	s_add_u32 s14, s14, s10
	s_addc_u32 s15, s15, s11
	s_add_u32 s10, s16, s10
	s_addc_u32 s11, s17, s11
	s_lshl_b32 s46, s2, 10
	v_and_b32_e32 v194, 63, v42
	s_cmp_lg_u32 0, -1
	v_lshlrev_b32_e32 v0, 4, v194
	s_cselect_b32 s4, 0, 0
	v_and_b32_e32 v195, 31, v42
	v_lshl_add_u64 v[182:183], s[14:15], 0, v[0:1]
	s_add_i32 s46, s46, s4
	s_mov_b32 s4, m0
	s_mov_b32 m0, s46
	s_nop 0
	global_load_lds_dwordx4 v[182:183], off
	s_mov_b32 m0, s4
	v_bfe_u32 v196, v42, 5, 1
	v_lshl_add_u64 v[82:83], s[10:11], 0, v[0:1]
	s_add_i32 s47, s46, 0x6000
	s_mov_b32 s4, m0
	s_mov_b32 m0, s47
	s_nop 0
	global_load_lds_dwordx4 v[82:83], off
	s_mov_b32 m0, s4
	v_lshlrev_b32_e32 v0, 10, v195
	v_lshl_add_u64 v[2:3], v[182:183], 0, s[38:39]
	s_add_i32 s4, s46, 0x2000
	s_mov_b32 s10, m0
	s_mov_b32 m0, s4
	s_nop 0
	global_load_lds_dwordx4 v[2:3], off
	s_mov_b32 m0, s10
	v_lshl_or_b32 v0, v196, 4, v0
	global_load_dwordx4 v[142:145], v0, s[8:9]
	global_load_dwordx4 v[134:137], v0, s[8:9] offset:32
	global_load_dwordx4 v[126:129], v0, s[8:9] offset:64
	global_load_dwordx4 v[118:121], v0, s[8:9] offset:96
	v_mov_b32_e32 v2, v1
	v_mov_b32_e32 v3, v1
	v_mov_b32_e32 v4, v1
	v_mov_b32_e32 v5, v1
	v_mov_b32_e32 v6, v1
	v_mov_b32_e32 v7, v1
	v_mov_b32_e32 v8, v1
	v_mov_b32_e32 v9, v1
	v_mov_b32_e32 v10, v1
	v_mov_b32_e32 v11, v1
	v_mov_b32_e32 v12, v1
	v_mov_b32_e32 v13, v1
	v_mov_b32_e32 v14, v1
	v_mov_b32_e32 v15, v1
	v_lshlrev_b32_e32 v0, 10, v196
	v_lshlrev_b32_e32 v16, 4, v195
	v_add3_u32 v202, 0, v0, v16
	v_mov_b32_e32 v0, v1
	v_mov_b64_e32 v[16:17], v[14:15]
	v_mov_b64_e32 v[14:15], v[12:13]
	v_mov_b64_e32 v[12:13], v[10:11]
	v_mov_b64_e32 v[10:11], v[8:9]
	v_mov_b64_e32 v[8:9], v[6:7]
	v_mov_b64_e32 v[6:7], v[4:5]
	v_mov_b64_e32 v[4:5], v[2:3]
	v_mov_b64_e32 v[2:3], v[0:1]
	v_lshl_add_u64 v[18:19], v[182:183], 0, s[42:43]
	s_add_i32 s4, s46, 0x4000
	s_mov_b32 s8, m0
	s_mov_b32 m0, s4
	s_nop 0
	global_load_lds_dwordx4 v[18:19], off
	s_mov_b32 m0, s8
	s_waitcnt vmcnt(3) lgkmcnt(0)
	s_barrier
	ds_read_b128 v[34:37], v202
	ds_read_b128 v[38:41], v202 offset:512
	v_lshlrev_b32_e32 v43, 1, v42
	v_lshlrev_b32_e32 v0, 3, v42
	v_and_b32_e32 v198, 32, v43
	s_lshl_b32 s5, s5, 2
	s_add_i32 s18, s5, 0
	v_lshl_add_u64 v[184:185], v[82:83], 0, s[38:39]
	v_and_b32_e32 v199, 24, v0
	v_add_u32_e32 v84, 0, v198
	s_mov_b32 s4, 1
	s_mov_b32 s14, 0
	s_movk_i32 s50, 0x2000
	s_movk_i32 s25, 0x4000
	s_andn2_b64 vcc, exec, s[0:1]
	v_cmp_gt_u32_e64 s[0:1], 32, v194
	v_lshlrev_b32_e32 v204, 4, v196
	v_lshl_add_u32 v200, v195, 2, s18
	s_waitcnt vmcnt(3) lgkmcnt(1)
	v_mfma_f32_32x32x16_bf16 v[18:33], v[34:37], v[142:145], v[2:17]
	s_waitcnt lgkmcnt(0)
	v_mfma_f32_32x32x16_bf16 v[2:17], v[38:41], v[142:145], v[2:17]
	ds_read_b128 v[34:37], v202 offset:2048
	ds_read_b128 v[38:41], v202 offset:2560
	s_waitcnt vmcnt(2) lgkmcnt(1)
	v_mfma_f32_32x32x16_bf16 v[18:33], v[34:37], v[134:137], v[18:33]
	s_waitcnt lgkmcnt(0)
	v_mfma_f32_32x32x16_bf16 v[2:17], v[38:41], v[134:137], v[2:17]
	ds_read_b128 v[34:37], v202 offset:4096
	ds_read_b128 v[38:41], v202 offset:4608
	s_waitcnt vmcnt(1) lgkmcnt(1)
	v_mfma_f32_32x32x16_bf16 v[18:33], v[34:37], v[126:129], v[18:33]
	ds_read_b128 v[34:37], v202 offset:6144
	s_waitcnt lgkmcnt(1)
	v_mfma_f32_32x32x16_bf16 v[2:17], v[38:41], v[126:129], v[2:17]
	ds_read_b128 v[38:41], v202 offset:6656
	s_waitcnt vmcnt(0) lgkmcnt(1)
	v_mfma_f32_32x32x16_bf16 v[18:33], v[34:37], v[118:121], v[18:33]
	v_lshlrev_b32_e32 v34, 4, v42
	v_and_b32_e32 v34, 0xc0, v34
	v_lshl_or_b32 v197, v196, 8, v34
	v_add3_u32 v203, v84, v199, v197
	s_waitcnt lgkmcnt(0)
	v_mfma_f32_32x32x16_bf16 v[2:17], v[38:41], v[118:121], v[2:17]
	s_nop 15
	s_nop 7
	s_nop 0
	v_max3_f32 v34, v18, v19, v2
	v_max3_f32 v35, v20, v21, v3
	s_nop 0
	v_max3_f32 v34, v34, v4, v5
	v_max3_f32 v35, v35, v24, v25
	s_nop 0
	v_max3_f32 v34, v34, v22, v23
	v_max3_f32 v35, v35, v8, v9
	s_nop 0
	v_max3_f32 v34, v34, v6, v7
	v_max3_f32 v35, v35, v28, v29
	s_nop 0
	v_max3_f32 v34, v34, v26, v27
	v_max3_f32 v35, v35, v12, v13
	s_nop 0
	v_max3_f32 v34, v34, v10, v11
	v_max3_f32 v35, v35, v32, v33
	s_nop 0
	v_max3_f32 v34, v34, v30, v31
	v_max3_f32 v35, v35, v16, v17
	s_nop 0
	v_max3_f32 v34, v34, v14, v15
	s_nop 0
	v_max_f32_e32 v34, v34, v35
	s_nop 0
	v_mov_b32_e32 v35, v34
	s_nop 1
	v_permlane32_swap_b32_e32 v34, v35
	v_max_f32_e32 v34, v34, v35
	s_nop 0
	v_add_f32_e32 v201, v1, v34
	v_sub_f32_e32 v18, v18, v34
	v_sub_f32_e32 v2, v2, v34
	v_sub_f32_e32 v19, v19, v34
	v_sub_f32_e32 v3, v3, v34
	v_sub_f32_e32 v20, v20, v34
	v_sub_f32_e32 v4, v4, v34
	v_sub_f32_e32 v21, v21, v34
	v_sub_f32_e32 v5, v5, v34
	v_sub_f32_e32 v22, v22, v34
	v_sub_f32_e32 v6, v6, v34
	v_sub_f32_e32 v23, v23, v34
	v_sub_f32_e32 v7, v7, v34
	v_sub_f32_e32 v24, v24, v34
	v_sub_f32_e32 v8, v8, v34
	v_sub_f32_e32 v25, v25, v34
	v_sub_f32_e32 v9, v9, v34
	v_sub_f32_e32 v26, v26, v34
	v_sub_f32_e32 v10, v10, v34
	v_sub_f32_e32 v27, v27, v34
	v_sub_f32_e32 v11, v11, v34
	v_sub_f32_e32 v28, v28, v34
	v_sub_f32_e32 v12, v12, v34
	v_sub_f32_e32 v29, v29, v34
	v_sub_f32_e32 v13, v13, v34
	v_sub_f32_e32 v30, v30, v34
	v_sub_f32_e32 v14, v14, v34
	v_sub_f32_e32 v31, v31, v34
	v_sub_f32_e32 v15, v15, v34
	v_sub_f32_e32 v32, v32, v34
	v_sub_f32_e32 v16, v16, v34
	v_sub_f32_e32 v33, v33, v34
	v_sub_f32_e32 v17, v17, v34
	s_nop 0
	v_xor_b32_e32 v34, 0x80000000, v201
	v_mov_b32_e32 v35, v34
	v_mov_b32_e32 v36, v34
	v_mov_b32_e32 v37, v34
	v_mov_b32_e32 v38, v34
	v_mov_b32_e32 v39, v34
	v_mov_b32_e32 v40, v34
	v_mov_b32_e32 v41, v34
	v_mov_b32_e32 v42, v34
	v_mov_b32_e32 v43, v34
	v_mov_b32_e32 v44, v34
	v_mov_b32_e32 v45, v34
	v_mov_b32_e32 v46, v34
	v_mov_b32_e32 v47, v34
	v_mov_b32_e32 v48, v34
	v_mov_b32_e32 v49, v34
	s_waitcnt vmcnt(0) lgkmcnt(0)
	s_barrier
	v_exp_f32_e32 v50, v2
	v_exp_f32_e32 v51, v3
	v_lshl_add_u64 v[2:3], v[182:183], 0, s[78:79]
	s_mov_b32 s5, m0
	s_mov_b32 m0, s46
	s_nop 0
	global_load_lds_dwordx4 v[2:3], off
	s_mov_b32 m0, s5
	s_add_i32 s5, s46, 0x8000
	s_mov_b32 s8, m0
	s_mov_b32 m0, s5
	s_nop 0
	global_load_lds_dwordx4 v[184:185], off
	s_mov_b32 m0, s8
	ds_read_b128 v[174:177], v202 offset:8192
	ds_read_b128 v[170:173], v202 offset:8704
	ds_read_b128 v[166:169], v202 offset:10240
	ds_read_b128 v[162:165], v202 offset:10752
	ds_read_b128 v[158:161], v202 offset:12288
	ds_read_b128 v[154:157], v202 offset:12800
	ds_read_b128 v[150:153], v202 offset:14336
	ds_read_b128 v[146:149], v202 offset:14848
	v_exp_f32_e32 v66, v18
	v_exp_f32_e32 v67, v19
	v_exp_f32_e32 v68, v20
	v_exp_f32_e32 v69, v21
	v_exp_f32_e32 v70, v22
	v_exp_f32_e32 v71, v23
	v_exp_f32_e32 v72, v24
	v_exp_f32_e32 v73, v25
	v_exp_f32_e32 v74, v26
	v_exp_f32_e32 v75, v27
	v_exp_f32_e32 v76, v28
	v_exp_f32_e32 v77, v29
	v_exp_f32_e32 v78, v30
	v_exp_f32_e32 v79, v31
	v_exp_f32_e32 v80, v32
	v_exp_f32_e32 v81, v33
	v_exp_f32_e32 v52, v4
	v_exp_f32_e32 v53, v5
	v_exp_f32_e32 v54, v6
	v_exp_f32_e32 v55, v7
	v_exp_f32_e32 v56, v8
	v_exp_f32_e32 v57, v9
	v_exp_f32_e32 v58, v10
	v_exp_f32_e32 v59, v11
	v_exp_f32_e32 v60, v12
	v_exp_f32_e32 v61, v13
	v_exp_f32_e32 v62, v14
	v_exp_f32_e32 v63, v15
	v_exp_f32_e32 v64, v16
	v_exp_f32_e32 v65, v17
	s_waitcnt vmcnt(2) lgkmcnt(0)
	s_barrier
	s_cbranch_vccnz .LBB0_499
	s_mov_b64 s[4:5], 0xa000
	v_mov_b32_e32 v205, 0
	v_readfirstlane_b32 s100, v182
	v_readfirstlane_b32 s101, v183
	v_sub_u32_e32 v186, v82, v182
	s_nop 3
	v_subrev_u32_e32 v188, s100, v182
	s_add_u32 s100, s100, 0x8000
	s_addc_u32 s101, s101, 0
	v_add_u32_e32 v186, v186, v188
	v_add_u32_e32 v187, 0xffffe000, v186
	v_add_u32_e32 v186, 0xffffc000, v186
	v_add_u32_e32 v189, 0x2000, v188
	s_movk_i32 s14, 0x4000
	s_movk_i32 s11, 0x2000
	s_mov_b32 s4, 0
	s_mov_b32 s10, 6
	v_mov_b32_e32 v18, 0
	v_mov_b32_e32 v19, v205
	v_mov_b32_e32 v20, v205
	v_mov_b32_e32 v21, v205
	v_mov_b32_e32 v22, v205
	v_mov_b32_e32 v23, v205
	v_mov_b32_e32 v24, v205
	v_mov_b32_e32 v25, v205
	v_mov_b32_e32 v26, v205
	v_mov_b32_e32 v27, v205
	v_mov_b32_e32 v28, v205
	v_mov_b32_e32 v29, v205
	v_mov_b32_e32 v30, v205
	v_mov_b32_e32 v31, v205
	v_mov_b32_e32 v32, v205
	v_mov_b32_e32 v33, v205
	v_mov_b32_e32 v2, v205
	v_mov_b32_e32 v3, v205
	v_mov_b32_e32 v4, v205
	v_mov_b32_e32 v5, v205
	v_mov_b32_e32 v6, v205
	v_mov_b32_e32 v7, v205
	v_mov_b32_e32 v8, v205
	v_mov_b32_e32 v9, v205
	v_mov_b32_e32 v10, v205
	v_mov_b32_e32 v11, v205
	v_mov_b32_e32 v12, v205
	v_mov_b32_e32 v13, v205
	v_mov_b32_e32 v14, v205
	v_mov_b32_e32 v15, v205
	v_mov_b32_e32 v16, v205
	v_mov_b32_e32 v17, v205
.LBB0_485:
	v_add_u32_e32 v190, s4, v203
	ds_read_b64_tr_b16 v[178:179], v190 offset:24576
	ds_read_b64_tr_b16 v[180:181], v190 offset:25088
	s_waitcnt lgkmcnt(9)
	v_mfma_f32_32x32x16_bf16 v[98:113], v[174:177], v[142:145], v[34:49]
	v_add_f32_e32 v82, v66, v67
	v_add_f32_e32 v82, v68, v82
	v_add_f32_e32 v82, v69, v82
	v_add_f32_e32 v82, v70, v82
	v_add_f32_e32 v82, v71, v82
	v_cvt_pk_bf16_f32 v138, v66, v67
	v_cvt_pk_bf16_f32 v139, v68, v69
	ds_read_b64_tr_b16 v[174:175], v190 offset:28672
	ds_read_b64_tr_b16 v[176:177], v190 offset:29184
	v_add_f32_e32 v66, v72, v82
	s_waitcnt lgkmcnt(10)
	v_mfma_f32_32x32x16_bf16 v[82:97], v[170:173], v[142:145], v[34:49]
	v_add_f32_e32 v66, v73, v66
	v_add_f32_e32 v66, v74, v66
	v_add_f32_e32 v114, v75, v66
	v_cvt_pk_bf16_f32 v140, v70, v71
	v_cvt_pk_bf16_f32 v141, v72, v73
	ds_read_b64_tr_b16 v[66:67], v190 offset:25600
	ds_read_b64_tr_b16 v[68:69], v190 offset:26112
	s_waitcnt lgkmcnt(11)
	v_mfma_f32_32x32x16_bf16 v[98:113], v[166:169], v[134:137], v[98:113]
	v_add_f32_e32 v70, v76, v114
	v_add_f32_e32 v70, v77, v70
	v_add_f32_e32 v70, v78, v70
	v_add_f32_e32 v114, v79, v70
	v_cvt_pk_bf16_f32 v130, v74, v75
	v_cvt_pk_bf16_f32 v131, v76, v77
	ds_read_b64_tr_b16 v[70:71], v190 offset:29696
	ds_read_b64_tr_b16 v[72:73], v190 offset:30208
	s_waitcnt lgkmcnt(12)
	v_mfma_f32_32x32x16_bf16 v[82:97], v[162:165], v[134:137], v[82:97]
	v_add_f32_e32 v74, v80, v114
	v_add_f32_e32 v74, v81, v74
	v_add_f32_e32 v74, v50, v74
	v_add_f32_e32 v114, v51, v74
	v_cvt_pk_bf16_f32 v132, v78, v79
	v_cvt_pk_bf16_f32 v133, v80, v81
	ds_read_b64_tr_b16 v[74:75], v190 offset:26624
	ds_read_b64_tr_b16 v[76:77], v190 offset:27136
	s_waitcnt lgkmcnt(13)
	v_mfma_f32_32x32x16_bf16 v[98:113], v[158:161], v[126:129], v[98:113]
	v_add_f32_e32 v78, v52, v114
	v_add_f32_e32 v78, v53, v78
	v_add_f32_e32 v78, v54, v78
	v_add_f32_e32 v78, v55, v78
	v_cvt_pk_bf16_f32 v122, v50, v51
	v_cvt_pk_bf16_f32 v123, v52, v53
	ds_read_b64_tr_b16 v[50:51], v190 offset:30720
	ds_read_b64_tr_b16 v[52:53], v190 offset:31232
	s_waitcnt lgkmcnt(14)
	v_mfma_f32_32x32x16_bf16 v[82:97], v[154:157], v[126:129], v[82:97]
	v_add_f32_e32 v78, v56, v78
	v_add_f32_e32 v78, v57, v78
	v_add_f32_e32 v78, v58, v78
	v_add_f32_e32 v78, v59, v78
	v_cvt_pk_bf16_f32 v124, v54, v55
	v_cvt_pk_bf16_f32 v125, v56, v57
	ds_read_b64_tr_b16 v[54:55], v190 offset:27648
	ds_read_b64_tr_b16 v[56:57], v190 offset:28160
	s_waitcnt lgkmcnt(14)
	v_mfma_f32_32x32x16_bf16 v[98:113], v[150:153], v[118:121], v[98:113]
	v_add_f32_e32 v78, v60, v78
	v_add_f32_e32 v78, v61, v78
	v_add_f32_e32 v78, v62, v78
	v_add_f32_e32 v78, v63, v78
	v_cvt_pk_bf16_f32 v114, v58, v59
	v_cvt_pk_bf16_f32 v115, v60, v61
	ds_read_b64_tr_b16 v[58:59], v190 offset:31744
	ds_read_b64_tr_b16 v[60:61], v190 offset:32256
	v_mfma_f32_32x32x16_bf16 v[82:97], v[146:149], v[118:121], v[82:97]
	v_add_f32_e32 v78, v64, v78
	v_add_f32_e32 v78, v65, v78
	v_cvt_pk_bf16_f32 v116, v62, v63
	v_cvt_pk_bf16_f32 v117, v64, v65
	s_add_i32 s4, s11, s46
	s_mov_b32 s5, m0
	s_mov_b32 m0, s4
	s_nop 0
	global_load_lds_dwordx4 v188, s[100:101]
	s_mov_b32 m0, s5
	s_add_i32 s4, s14, s47
	s_mov_b32 s5, m0
	s_mov_b32 m0, s4
	s_nop 0
	global_load_lds_dwordx4 v186, s[100:101]
	s_mov_b32 m0, s5
	s_cmp_lg_u32 s99, 0
	s_cbranch_scc1 .Lnomax_1
	v_max_f32_e32 v62, v99, v99
	v_max_f32_e32 v63, v98, v98
	v_max_f32_e32 v62, v63, v62
	v_max3_f32 v63, v100, v101, v83
	v_max3_f32 v62, v62, v82, v84
	v_max3_f32 v62, v62, v85, v102
	v_max3_f32 v63, v63, v104, v105
	v_max3_f32 v62, v62, v103, v86
	v_max3_f32 v63, v63, v88, v89
	v_max3_f32 v62, v62, v87, v106
	v_max3_f32 v63, v63, v108, v109
	v_max3_f32 v62, v62, v107, v90
	v_max3_f32 v63, v63, v92, v93
	v_max3_f32 v62, v62, v91, v110
	v_max3_f32 v63, v63, v112, v113
	v_max3_f32 v62, v62, v111, v94
	v_max3_f32 v63, v63, v96, v97
	v_max3_f32 v62, v62, v95, v63
	v_mov_b32_e32 v63, v62
	s_nop 1
	v_permlane32_swap_b32_e32 v62, v63
	v_max_f32_e32 v63, v63, v63
	v_max_f32_e32 v62, v62, v62
	v_max_f32_e32 v62, v62, v63
	v_cmp_lt_f32_e32 vcc, s93, v62
	s_cmp_lg_u64 vcc, 0
	v_add_f32_e32 v190, v205, v78
	s_cselect_b64 s[4:5], -1, 0
	s_cbranch_vccnz .LBB0_493
.LBB0_486:
	s_waitcnt lgkmcnt(14)
	v_mfma_f32_32x32x16_bf16 v[18:33], v[138:141], v[178:181], v[18:33]
	v_exp_f32_e32 v98, v98
	v_exp_f32_e32 v99, v99
	v_exp_f32_e32 v100, v100
	v_exp_f32_e32 v101, v101
	s_waitcnt lgkmcnt(12)
	v_mfma_f32_32x32x16_bf16 v[2:17], v[138:141], v[174:177], v[2:17]
	v_exp_f32_e32 v102, v102
	v_exp_f32_e32 v103, v103
	v_exp_f32_e32 v104, v104
	v_exp_f32_e32 v105, v105
	v_add_u32_e32 v78, s14, v202
	ds_read_b128 v[62:65], v78
	ds_read_b128 v[174:177], v78 offset:512
	s_waitcnt lgkmcnt(12)
	v_mfma_f32_32x32x16_bf16 v[18:33], v[130:133], v[66:69], v[18:33]
	v_exp_f32_e32 v106, v106
	v_exp_f32_e32 v107, v107
	v_exp_f32_e32 v108, v108
	v_exp_f32_e32 v109, v109
	ds_read_b128 v[178:181], v78 offset:2048
	ds_read_b128 v[170:173], v78 offset:2560
	s_waitcnt lgkmcnt(12)
	v_mfma_f32_32x32x16_bf16 v[2:17], v[130:133], v[70:73], v[2:17]
	v_exp_f32_e32 v110, v110
	v_exp_f32_e32 v111, v111
	v_exp_f32_e32 v112, v112
	v_exp_f32_e32 v113, v113
	ds_read_b128 v[166:169], v78 offset:4096
	ds_read_b128 v[162:165], v78 offset:4608
	s_waitcnt lgkmcnt(12)
	v_mfma_f32_32x32x16_bf16 v[18:33], v[122:125], v[74:77], v[18:33]
	v_exp_f32_e32 v82, v82
	v_exp_f32_e32 v83, v83
	v_exp_f32_e32 v84, v84
	v_exp_f32_e32 v85, v85
	ds_read_b128 v[158:161], v78 offset:6144
	ds_read_b128 v[154:157], v78 offset:6656
	s_waitcnt lgkmcnt(12)
	v_mfma_f32_32x32x16_bf16 v[2:17], v[122:125], v[50:53], v[2:17]
	v_exp_f32_e32 v86, v86
	v_exp_f32_e32 v87, v87
	v_exp_f32_e32 v88, v88
	v_exp_f32_e32 v89, v89
	s_waitcnt lgkmcnt(10)
	v_mfma_f32_32x32x16_bf16 v[18:33], v[114:117], v[54:57], v[18:33]
	v_exp_f32_e32 v90, v90
	v_exp_f32_e32 v91, v91
	v_exp_f32_e32 v92, v92
	v_exp_f32_e32 v93, v93
	s_waitcnt lgkmcnt(8)
	v_mfma_f32_32x32x16_bf16 v[2:17], v[114:117], v[58:61], v[2:17]
	v_exp_f32_e32 v94, v94
	v_exp_f32_e32 v95, v95
	v_exp_f32_e32 v96, v96
	v_exp_f32_e32 v97, v97
	s_waitcnt vmcnt(2) lgkmcnt(0)
	s_barrier
	s_andn2_b64 vcc, exec, s[4:5]
	s_cbranch_vccnz .LBB0_488
	s_waitcnt lgkmcnt(0)
	v_add_u32_e32 v191, s18, v204
	ds_read_b128 v[50:53], v191 offset:49248
	ds_read_b128 v[54:57], v191 offset:49216
	ds_read_b128 v[58:61], v191 offset:49184
	ds_read_b128 v[66:69], v191 offset:49152
	s_waitcnt lgkmcnt(3)
	v_pk_mul_f32 v[30:31], v[30:31], v[50:51]
	s_waitcnt lgkmcnt(2)
	v_pk_mul_f32 v[26:27], v[26:27], v[54:55]
	s_waitcnt lgkmcnt(1)
	v_pk_mul_f32 v[22:23], v[22:23], v[58:59]
	v_pk_mul_f32 v[32:33], v[32:33], v[52:53]
	v_pk_mul_f32 v[28:29], v[28:29], v[56:57]
	v_pk_mul_f32 v[24:25], v[24:25], v[60:61]
	s_waitcnt lgkmcnt(0)
	v_pk_mul_f32 v[20:21], v[20:21], v[68:69]
	v_pk_mul_f32 v[18:19], v[18:19], v[66:67]
	v_pk_mul_f32 v[14:15], v[14:15], v[50:51]
	v_pk_mul_f32 v[10:11], v[10:11], v[54:55]
	v_pk_mul_f32 v[6:7], v[6:7], v[58:59]
	v_pk_mul_f32 v[16:17], v[16:17], v[52:53]
	v_pk_mul_f32 v[12:13], v[12:13], v[56:57]
	v_pk_mul_f32 v[8:9], v[8:9], v[60:61]
	v_pk_mul_f32 v[4:5], v[4:5], v[68:69]
	v_pk_mul_f32 v[2:3], v[2:3], v[66:67]
.LBB0_488:
	s_add_i32 s4, s14, 0x2000
	s_cmpk_lg_i32 s14, 0x4000
	s_cselect_b32 s50, s4, 0
	v_add_u32_e32 v192, s11, v203
	ds_read_b64_tr_b16 v[150:151], v192 offset:24576
	ds_read_b64_tr_b16 v[152:153], v192 offset:25088
	s_waitcnt lgkmcnt(9)
	v_mfma_f32_32x32x16_bf16 v[66:81], v[62:65], v[142:145], v[34:49]
	v_add_f32_e32 v50, v98, v99
	v_add_f32_e32 v50, v100, v50
	v_add_f32_e32 v50, v101, v50
	v_add_f32_e32 v50, v102, v50
	v_add_f32_e32 v50, v103, v50
	v_cvt_pk_bf16_f32 v138, v98, v99
	v_cvt_pk_bf16_f32 v139, v100, v101
	ds_read_b64_tr_b16 v[146:147], v192 offset:28672
	ds_read_b64_tr_b16 v[148:149], v192 offset:29184
	v_add_f32_e32 v50, v104, v50
	v_add_f32_e32 v50, v105, v50
	v_add_f32_e32 v50, v106, v50
	v_add_f32_e32 v114, v107, v50
	s_waitcnt lgkmcnt(10)
	v_mfma_f32_32x32x16_bf16 v[50:65], v[174:177], v[142:145], v[34:49]
	v_cvt_pk_bf16_f32 v140, v102, v103
	v_cvt_pk_bf16_f32 v141, v104, v105
	ds_read_b64_tr_b16 v[98:99], v192 offset:25600
	ds_read_b64_tr_b16 v[100:101], v192 offset:26112
	s_waitcnt lgkmcnt(11)
	v_mfma_f32_32x32x16_bf16 v[66:81], v[178:181], v[134:137], v[66:81]
	v_add_f32_e32 v102, v108, v114
	v_add_f32_e32 v102, v109, v102
	v_add_f32_e32 v102, v110, v102
	v_add_f32_e32 v114, v111, v102
	v_cvt_pk_bf16_f32 v130, v106, v107
	v_cvt_pk_bf16_f32 v131, v108, v109
	ds_read_b64_tr_b16 v[102:103], v192 offset:29696
	ds_read_b64_tr_b16 v[104:105], v192 offset:30208
	s_waitcnt lgkmcnt(12)
	v_mfma_f32_32x32x16_bf16 v[50:65], v[170:173], v[134:137], v[50:65]
	v_add_f32_e32 v106, v112, v114
	v_add_f32_e32 v106, v113, v106
	v_add_f32_e32 v106, v82, v106
	v_add_f32_e32 v114, v83, v106
	v_cvt_pk_bf16_f32 v132, v110, v111
	v_cvt_pk_bf16_f32 v133, v112, v113
	ds_read_b64_tr_b16 v[106:107], v192 offset:26624
	ds_read_b64_tr_b16 v[108:109], v192 offset:27136
	s_waitcnt lgkmcnt(13)
	v_mfma_f32_32x32x16_bf16 v[66:81], v[166:169], v[126:129], v[66:81]
	v_add_f32_e32 v110, v84, v114
	v_add_f32_e32 v110, v85, v110
	v_add_f32_e32 v110, v86, v110
	v_add_f32_e32 v110, v87, v110
	v_cvt_pk_bf16_f32 v122, v82, v83
	v_cvt_pk_bf16_f32 v123, v84, v85
	ds_read_b64_tr_b16 v[82:83], v192 offset:30720
	ds_read_b64_tr_b16 v[84:85], v192 offset:31232
	s_waitcnt lgkmcnt(14)
	v_mfma_f32_32x32x16_bf16 v[50:65], v[162:165], v[126:129], v[50:65]
	v_add_f32_e32 v110, v88, v110
	v_add_f32_e32 v110, v89, v110
	v_add_f32_e32 v110, v90, v110
	v_add_f32_e32 v110, v91, v110
	v_cvt_pk_bf16_f32 v124, v86, v87
	v_cvt_pk_bf16_f32 v125, v88, v89
	ds_read_b64_tr_b16 v[86:87], v192 offset:27648
	ds_read_b64_tr_b16 v[88:89], v192 offset:28160
	s_waitcnt lgkmcnt(14)
	v_mfma_f32_32x32x16_bf16 v[66:81], v[158:161], v[118:121], v[66:81]
	v_add_f32_e32 v110, v92, v110
	v_add_f32_e32 v110, v93, v110
	v_add_f32_e32 v110, v94, v110
	v_add_f32_e32 v110, v95, v110
	v_cvt_pk_bf16_f32 v114, v90, v91
	v_cvt_pk_bf16_f32 v115, v92, v93
	ds_read_b64_tr_b16 v[90:91], v192 offset:31744
	ds_read_b64_tr_b16 v[92:93], v192 offset:32256
	v_mfma_f32_32x32x16_bf16 v[50:65], v[154:157], v[118:121], v[50:65]
	v_add_f32_e32 v110, v96, v110
	v_add_f32_e32 v110, v97, v110
	v_cvt_pk_bf16_f32 v116, v94, v95
	v_cvt_pk_bf16_f32 v117, v96, v97
	s_cmp_lg_u32 s99, 0
	s_cbranch_scc1 .Lnomax_2a
	v_max_f32_e32 v94, v67, v67
	v_max_f32_e32 v95, v66, v66
	v_max_f32_e32 v94, v95, v94
	s_nop 3
	v_max3_f32 v95, v68, v69, v51
	v_max3_f32 v94, v94, v50, v52
	v_max3_f32 v94, v94, v53, v70
	v_max3_f32 v95, v95, v72, v73
	v_max3_f32 v94, v94, v71, v54
	v_max3_f32 v95, v95, v56, v57
	v_max3_f32 v94, v94, v55, v74
	v_max3_f32 v95, v95, v76, v77
	v_max3_f32 v94, v94, v75, v58
	v_max3_f32 v95, v95, v60, v61
	v_max3_f32 v94, v94, v59, v78
	v_max3_f32 v95, v95, v80, v81
	v_max3_f32 v94, v94, v79, v62
	v_max3_f32 v95, v95, v64, v65
	v_max3_f32 v94, v94, v63, v95
	v_mov_b32_e32 v95, v94
	s_nop 1
	v_permlane32_swap_b32_e32 v94, v95
	v_max_f32_e32 v95, v95, v95
	v_max_f32_e32 v94, v94, v94
.Lnomax_2a:
	s_add_i32 s4, s14, s46
	s_mov_b32 s5, m0
	s_mov_b32 m0, s4
	s_nop 0
	global_load_lds_dwordx4 v189, s[100:101]
	s_mov_b32 m0, s5
	v_max_f32_e32 v94, v94, v95
	s_add_i32 s4, s50, s47
	s_mov_b32 s5, m0
	s_mov_b32 m0, s4
	s_nop 0
	global_load_lds_dwordx4 v187, s[100:101]
	s_mov_b32 m0, s5
	s_cmp_lg_u32 s99, 0
	s_cbranch_scc1 .Lnomax_2b
	v_cmp_lt_f32_e32 vcc, s93, v94
	s_cmp_lg_u64 vcc, 0
	v_add_f32_e32 v205, v190, v110
	s_cselect_b64 s[4:5], -1, 0
	s_cbranch_vccnz .LBB0_496
.LBB0_489:
	s_waitcnt lgkmcnt(14)
	v_mfma_f32_32x32x16_bf16 v[18:33], v[138:141], v[150:153], v[18:33]
	v_exp_f32_e32 v66, v66
	v_exp_f32_e32 v67, v67
	v_exp_f32_e32 v68, v68
	v_exp_f32_e32 v69, v69
	s_waitcnt lgkmcnt(12)
	v_mfma_f32_32x32x16_bf16 v[2:17], v[138:141], v[146:149], v[2:17]
	v_exp_f32_e32 v70, v70
	v_exp_f32_e32 v71, v71
	v_exp_f32_e32 v72, v72
	v_exp_f32_e32 v73, v73
	v_add_u32_e32 v94, s50, v202
	ds_read_b128 v[174:177], v94
	ds_read_b128 v[170:173], v94 offset:512
	s_waitcnt lgkmcnt(12)
	v_mfma_f32_32x32x16_bf16 v[18:33], v[130:133], v[98:101], v[18:33]
	v_exp_f32_e32 v74, v74
	v_exp_f32_e32 v75, v75
	v_exp_f32_e32 v76, v76
	v_exp_f32_e32 v77, v77
	ds_read_b128 v[166:169], v94 offset:2048
	ds_read_b128 v[162:165], v94 offset:2560
	s_waitcnt lgkmcnt(12)
	v_mfma_f32_32x32x16_bf16 v[2:17], v[130:133], v[102:105], v[2:17]
	v_exp_f32_e32 v78, v78
	v_exp_f32_e32 v79, v79
	v_exp_f32_e32 v80, v80
	v_exp_f32_e32 v81, v81
	ds_read_b128 v[158:161], v94 offset:4096
	ds_read_b128 v[154:157], v94 offset:4608
	s_waitcnt lgkmcnt(12)
	v_mfma_f32_32x32x16_bf16 v[18:33], v[122:125], v[106:109], v[18:33]
	v_exp_f32_e32 v50, v50
	v_exp_f32_e32 v51, v51
	v_exp_f32_e32 v52, v52
	v_exp_f32_e32 v53, v53
	ds_read_b128 v[150:153], v94 offset:6144
	ds_read_b128 v[146:149], v94 offset:6656
	s_waitcnt lgkmcnt(12)
	v_mfma_f32_32x32x16_bf16 v[2:17], v[122:125], v[82:85], v[2:17]
	v_exp_f32_e32 v54, v54
	v_exp_f32_e32 v55, v55
	v_exp_f32_e32 v56, v56
	v_exp_f32_e32 v57, v57
	s_waitcnt lgkmcnt(10)
	v_mfma_f32_32x32x16_bf16 v[18:33], v[114:117], v[86:89], v[18:33]
	v_exp_f32_e32 v58, v58
	v_exp_f32_e32 v59, v59
	v_exp_f32_e32 v60, v60
	v_exp_f32_e32 v61, v61
	s_waitcnt lgkmcnt(8)
	v_mfma_f32_32x32x16_bf16 v[2:17], v[114:117], v[90:93], v[2:17]
	v_exp_f32_e32 v62, v62
	v_exp_f32_e32 v63, v63
	v_exp_f32_e32 v64, v64
	v_exp_f32_e32 v65, v65
	s_waitcnt vmcnt(2) lgkmcnt(0)
	s_barrier
	s_andn2_b64 vcc, exec, s[4:5]
	s_cbranch_vccnz .LBB0_491
	s_waitcnt lgkmcnt(0)
	v_add_u32_e32 v191, s18, v204
	ds_read_b128 v[82:85], v191 offset:49248
	ds_read_b128 v[86:89], v191 offset:49216
	ds_read_b128 v[90:93], v191 offset:49152
	ds_read_b128 v[94:97], v191 offset:49184
	s_waitcnt lgkmcnt(3)
	v_pk_mul_f32 v[32:33], v[32:33], v[84:85]
	v_pk_mul_f32 v[30:31], v[30:31], v[82:83]
	s_waitcnt lgkmcnt(2)
	v_pk_mul_f32 v[28:29], v[28:29], v[88:89]
	v_pk_mul_f32 v[26:27], v[26:27], v[86:87]
	s_waitcnt lgkmcnt(0)
	v_pk_mul_f32 v[24:25], v[24:25], v[96:97]
	v_pk_mul_f32 v[22:23], v[22:23], v[94:95]
	v_pk_mul_f32 v[20:21], v[20:21], v[92:93]
	v_pk_mul_f32 v[18:19], v[18:19], v[90:91]
	v_pk_mul_f32 v[16:17], v[16:17], v[84:85]
	v_pk_mul_f32 v[14:15], v[14:15], v[82:83]
	v_pk_mul_f32 v[12:13], v[12:13], v[88:89]
	v_pk_mul_f32 v[10:11], v[10:11], v[86:87]
	v_pk_mul_f32 v[8:9], v[8:9], v[96:97]
	v_pk_mul_f32 v[6:7], v[6:7], v[94:95]
	v_pk_mul_f32 v[4:5], v[4:5], v[92:93]
	v_pk_mul_f32 v[2:3], v[2:3], v[90:91]
.LBB0_491:
	s_add_u32 s100, s100, s42
	s_addc_u32 s101, s101, s43
	s_add_i32 s4, s50, 0x2000
	s_cmpk_lg_i32 s50, 0x4000
	s_cselect_b32 s25, s4, 0
	s_add_i32 s4, s10, 2
	s_cmp_ge_u32 s4, s19
	s_cbranch_scc1 .LBB0_500
	s_mov_b32 s10, s4
	s_mov_b32 s4, s14
	s_mov_b32 s11, s50
	s_mov_b32 s14, s25
	s_branch .LBB0_485
